# v42 + E6D: in FF1 the workgroups that own 8 tiles (bx>=128, layers with context rows) start half a tile late so store bursts of the two halves interleave
# baseline (speedup 1.0000x reference)
; #define PG8_STAGE(bufoff, gbase, voff) do { _Pragma("unroll") for (int _i = 0; _i < 2; ++_i) \
;         __builtin_amdgcn_global_load_lds((const unsigned*)((const char*)(gbase) + (voff)[_i]), (PG8_LAS unsigned*)(lds + (bufoff) + ldsw + _i * 8192), 16, 0, 0); } while (0)
; #define PG8_WAIT_V(n) asm volatile("s_waitcnt vmcnt(" #n ")" ::: "memory")
; #define PG8_BAR __builtin_amdgcn_s_barrier()
; template <class Epi, class Sched, bool ALIGN_EPI = false, bool SP2 = false>
; __device__ __forceinline__ void gemm_phase(PG8_LAS unsigned char* lds, const Gemm g, const Sched& S, const Epi& E) {
;     ...
;     if constexpr (SP2) {
;         PG8_STAGE(PG8_SB(0, 0), cB, voffB); PG8_STAGE(PG8_SB(0, 1), cB + hstep, voffB); PG8_STAGE(PG8_SA(0, 0), cA, voffA); PG8_STAGE(PG8_SA(0, 1), cA + hstep, voffA);
;         if (wr == 1) PG8_BAR;
;         PG8_WAIT_V(2); PG8_BAR;
;         PG8_STAGE(PG8_SB(1, 0), cB + kstep, voffB); PG8_STAGE(PG8_SA(1, 0), cA + kstep, voffA); PG8_STAGE(PG8_SB(1, 1), cB + hstep + kstep, voffB);
;         PG8_WAIT_V(6); PG8_BAR;
;     } else {
;         PG8_STAGE(PG8_SB(0, 0), cB, voffB); PG8_STAGE(PG8_SA(0, 0), cA, voffA); PG8_STAGE(PG8_SB(0, 1), cB + hstep, voffB); PG8_STAGE(PG8_SA(0, 1), cA + hstep, voffA);
;         if (wr == 1) PG8_BAR;
;         PG8_WAIT_V(4); PG8_BAR;
;         PG8_STAGE(PG8_SB(1, 0), cB + kstep, voffB); PG8_STAGE(PG8_SA(1, 0), cA + kstep, voffA); PG8_STAGE(PG8_SB(1, 1), cB + hstep + kstep, voffB);
;         PG8_WAIT_V(6); PG8_BAR;
;     }
.LBB0_1334:
	v_lshrrev_b32_e32 v18, 1, v16
	v_and_b32_e32 v18, 24, v18
	v_and_b32_e32 v17, 15, v16
	v_lshlrev_b32_e32 v19, 1, v18
	v_lshlrev_b32_e32 v16, 2, v16
	s_and_b32 s20, s18, 3
	v_lshl_or_b32 v158, s1, 6, v17
	v_lshl_or_b32 v17, v17, 6, v19
	s_lshl_b32 s1, s1, 13
	v_and_b32_e32 v16, 32, v16
	s_add_i32 m0, s29, 0x18000
	v_lshl_add_u64 v[8:9], v[8:9], 0, s[72:73]
	v_bitop3_b32 v19, v17, s1, v16 bitop3:0xde
	s_lshl_b32 s1, s20, 12
	s_waitcnt vmcnt(2)
	s_barrier
	global_load_lds_dwordx4 v[8:9], off
	v_lshl_add_u64 v[6:7], v[6:7], 0, s[72:73]
	s_add_i32 m0, s29, 0x1a000
	s_add_i32 s50, s29, 0x8000
	s_add_i32 s51, s29, 0xa000
	global_load_lds_dwordx4 v[6:7], off
	v_lshl_add_u64 v[2:3], v[2:3], 0, s[72:73]
	s_mov_b32 m0, s50
	s_add_u32 s18, s36, 0x40080
	global_load_lds_dwordx4 v[2:3], off
	v_lshl_add_u64 v[2:3], v[4:5], 0, s[72:73]
	s_mov_b32 m0, s51
	s_addc_u32 s19, s37, 0
	global_load_lds_dwordx4 v[2:3], off
	s_add_i32 m0, s29, 0x1c000
	v_lshl_add_u64 v[2:3], s[18:19], 0, v[0:1]
	global_load_lds_dwordx4 v[2:3], off
	v_lshl_add_u64 v[2:3], s[18:19], 0, v[146:147]
	s_add_i32 m0, s29, 0x1e000
	s_cmpk_lt_u32 s0, 0x100
	global_load_lds_dwordx4 v[2:3], off
	v_lshlrev_b32_e32 v2, 14, v14
	v_and_b32_e32 v2, 0xffff8000, v2
	v_lshl_add_u32 v2, v13, 11, v2
	v_and_b32_e32 v3, 1, v14
	v_lshl_or_b32 v2, v3, 6, v2
	v_lshl_add_u32 v152, v15, 1, v2
	v_lshlrev_b32_e32 v2, 14, v10
	v_and_b32_e32 v2, 0xffff8000, v2
	s_waitcnt vmcnt(6)
	v_lshl_add_u32 v2, v11, 11, v2
	v_and_b32_e32 v3, 1, v10
	v_lshl_or_b32 v2, v3, 6, v2
	v_bitop3_b32 v159, v17, s1, v16 bitop3:0xde
	s_cselect_b64 s[18:19], -1, 0
	v_lshl_or_b32 v160, s20, 6, v18
	v_mov_b32_e32 v153, v1
	v_lshl_add_u32 v154, v12, 1, v2
	v_mov_b32_e32 v155, v1
	s_mov_b32 s52, 0
	v_add_u32_e32 v161, 0, v19
	s_barrier
	s_cmp_lt_u32 s79, 0x80
	s_cbranch_scc1 .Le6d_skip
	v_readlane_b32 s100, v253, 43
	s_nop 3
	s_cmp_lg_u32 s100, 0
	s_cbranch_scc1 .Le6d_skip
	s_sleep 127
	s_sleep 127
	s_sleep 127
.Le6d_skip:
	s_branch .LBB0_1337
.LBB0_1335:
	s_mov_b64 s[0:1], 0
